# P4 delta-rule step B (K K^T -> L, Q K^T -> intra) hand-written, branch-free: gates fetched in 9 LDS reads instead of one exposed read per element
# speedup vs baseline: 1.0180x; 1.0003x over previous
.LBB0_667:
	s_waitcnt vmcnt(8)
	v_lshlrev_b32_e32 v209, 16, v44
	v_lshlrev_b32_e32 v213, 16, v164
	s_waitcnt lgkmcnt(0)
	v_sub_f32_e32 v32, v200, v32
	v_lshlrev_b32_e32 v47, 16, v152
	v_and_b32_e32 v163, 0xffff0000, v152
	v_lshlrev_b32_e32 v207, 16, v37
	v_lshlrev_b32_e32 v211, 16, v45
	v_lshlrev_b32_e32 v218, 16, v172
	v_and_b32_e32 v219, 0xffff0000, v172
	v_lshlrev_b32_e32 v172, 16, v175
	v_and_b32_e32 v152, 0xffff0000, v175
	v_lshlrev_b32_e32 v228, 16, v182
	v_and_b32_e32 v244, 0xffff0000, v182
	v_mul_f32_e32 v175, v60, v209
	v_mul_f32_e32 v182, v70, v213
	v_mul_f32_e32 v32, 0x3fb8aa3b, v32
	v_and_b32_e32 v210, 0xffff0000, v44
	v_and_b32_e32 v214, 0xffff0000, v164
	v_fmac_f32_e32 v175, v54, v207
	v_fmac_f32_e32 v182, v62, v211
	v_exp_f32_e32 v202, v32
	v_and_b32_e32 v208, 0xffff0000, v37
	v_lshlrev_b32_e32 v32, 16, v41
	v_and_b32_e32 v33, 0xffff0000, v41
	v_lshlrev_b32_e32 v174, 16, v40
	v_and_b32_e32 v168, 0xffff0000, v40
	v_and_b32_e32 v212, 0xffff0000, v45
	v_lshlrev_b32_e32 v40, 16, v170
	v_and_b32_e32 v41, 0xffff0000, v170
	v_lshlrev_b32_e32 v34, 16, v180
	v_and_b32_e32 v35, 0xffff0000, v180
	v_lshlrev_b32_e32 v180, 16, v184
	v_and_b32_e32 v170, 0xffff0000, v184
	v_lshlrev_b32_e32 v245, 16, v183
	v_and_b32_e32 v246, 0xffff0000, v183
	v_add_f32_e32 v175, v175, v182
	v_mul_f32_e32 v183, v61, v210
	v_mul_f32_e32 v184, v71, v214
	v_mul_f32_e32 v182, 0xbfb8aa3b, v175
	v_fmac_f32_e32 v183, v55, v208
	v_fmac_f32_e32 v184, v63, v212
	v_exp_f32_e32 v182, v182
	v_add_f32_e32 v183, v183, v184
	v_mul_f32_e32 v184, 0xbfb8aa3b, v183
	v_exp_f32_e32 v184, v184
	v_add_f32_e32 v182, 1.0, v182
	v_rcp_f32_e32 v182, v182
	v_lshlrev_b32_e32 v215, 16, v166
	v_add_f32_e32 v184, 1.0, v184
	v_rcp_f32_e32 v184, v184
	v_mul_f32_e32 v234, v175, v182
	v_mul_f32_e32 v175, v60, v211
	v_mul_f32_e32 v182, v70, v215
	v_and_b32_e32 v216, 0xffff0000, v166
	v_fmac_f32_e32 v175, v54, v209
	v_fmac_f32_e32 v182, v62, v213
	v_mul_f32_e32 v235, v183, v184
	v_add_f32_e32 v175, v175, v182
	v_mul_f32_e32 v183, v61, v212
	v_mul_f32_e32 v184, v71, v216
	v_mul_f32_e32 v182, 0xbfb8aa3b, v175
	v_fmac_f32_e32 v183, v55, v210
	v_fmac_f32_e32 v184, v63, v214
	v_exp_f32_e32 v182, v182
	v_add_f32_e32 v183, v183, v184
	v_mul_f32_e32 v184, 0xbfb8aa3b, v183
	v_exp_f32_e32 v184, v184
	v_add_f32_e32 v182, 1.0, v182
	v_rcp_f32_e32 v182, v182
	v_lshlrev_b32_e32 v158, 16, v154
	v_add_f32_e32 v184, 1.0, v184
	v_rcp_f32_e32 v184, v184
	v_and_b32_e32 v159, 0xffff0000, v154
	v_lshlrev_b32_e32 v178, 16, v167
	v_and_b32_e32 v154, 0xffff0000, v167
	v_lshlrev_b32_e32 v166, 16, v169
	v_and_b32_e32 v167, 0xffff0000, v169
	v_lshlrev_b32_e32 v169, 16, v171
	v_mul_f32_e32 v229, v175, v182
	v_mul_f32_e32 v175, v60, v213
	v_mul_f32_e32 v182, v70, v169
	v_and_b32_e32 v217, 0xffff0000, v171
	v_fmac_f32_e32 v175, v54, v211
	v_fmac_f32_e32 v182, v62, v215
	v_mul_f32_e32 v230, v183, v184
	v_add_f32_e32 v175, v175, v182
	v_mul_f32_e32 v183, v61, v214
	v_mul_f32_e32 v184, v71, v217
	v_mul_f32_e32 v182, 0xbfb8aa3b, v175
	v_fmac_f32_e32 v183, v55, v212
	v_fmac_f32_e32 v184, v63, v216
	v_exp_f32_e32 v182, v182
	v_add_f32_e32 v183, v183, v184
	v_mul_f32_e32 v184, 0xbfb8aa3b, v183
	v_exp_f32_e32 v184, v184
	v_add_f32_e32 v182, 1.0, v182
	v_rcp_f32_e32 v182, v182
	v_lshlrev_b32_e32 v247, 16, v203
	v_add_f32_e32 v184, 1.0, v184
	v_rcp_f32_e32 v184, v184
	v_mul_f32_e32 v224, v175, v182
	v_mul_f32_e32 v175, v60, v215
	v_mul_f32_e32 v182, v70, v218
	v_fmac_f32_e32 v175, v54, v213
	v_fmac_f32_e32 v182, v62, v169
	v_mul_f32_e32 v225, v183, v184
	v_add_f32_e32 v175, v175, v182
	v_mul_f32_e32 v183, v61, v216
	v_mul_f32_e32 v184, v71, v219
	v_mul_f32_e32 v182, 0xbfb8aa3b, v175
	v_fmac_f32_e32 v183, v55, v214
	v_fmac_f32_e32 v184, v63, v217
	v_exp_f32_e32 v182, v182
	v_add_f32_e32 v183, v183, v184
	v_mul_f32_e32 v184, 0xbfb8aa3b, v183
	v_exp_f32_e32 v184, v184
	v_add_f32_e32 v182, 1.0, v182
	v_rcp_f32_e32 v182, v182
	v_and_b32_e32 v248, 0xffff0000, v203
	v_add_f32_e32 v184, 1.0, v184
	v_rcp_f32_e32 v184, v184
	v_mul_f32_e32 v220, v175, v182
	v_mul_f32_e32 v175, v60, v169
	v_mul_f32_e32 v182, v70, v228
	v_fmac_f32_e32 v175, v54, v215
	v_fmac_f32_e32 v182, v62, v218
	v_mul_f32_e32 v221, v183, v184
	v_add_f32_e32 v175, v175, v182
	v_mul_f32_e32 v183, v61, v217
	v_mul_f32_e32 v184, v71, v244
	v_mul_f32_e32 v182, 0xbfb8aa3b, v175
	v_fmac_f32_e32 v183, v55, v216
	v_fmac_f32_e32 v184, v63, v219
	v_exp_f32_e32 v182, v182
	v_add_f32_e32 v183, v183, v184
	v_mul_f32_e32 v184, 0xbfb8aa3b, v183
	v_exp_f32_e32 v184, v184
	v_add_f32_e32 v182, 1.0, v182
	v_rcp_f32_e32 v182, v182
	v_add_f32_e32 v184, 1.0, v184
	v_rcp_f32_e32 v184, v184
	v_mul_f32_e32 v214, v175, v182
	v_mul_f32_e32 v175, v60, v218
	v_fmac_f32_e32 v175, v54, v169
	v_mul_f32_e32 v169, v70, v245
	v_mul_f32_e32 v215, v183, v184
	v_fmac_f32_e32 v169, v62, v228
	v_mul_f32_e32 v182, v61, v219
	v_mul_f32_e32 v183, v71, v246
	v_add_f32_e32 v169, v175, v169
	v_fmac_f32_e32 v182, v55, v217
	v_fmac_f32_e32 v183, v63, v244
	v_mul_f32_e32 v175, 0xbfb8aa3b, v169
	v_add_f32_e32 v182, v182, v183
	v_exp_f32_e32 v175, v175
	v_mul_f32_e32 v183, 0xbfb8aa3b, v182
	v_exp_f32_e32 v183, v183
	s_add_i32 s64, s89, 0
	v_add_f32_e32 v175, 1.0, v175
	v_rcp_f32_e32 v175, v175
	v_add_f32_e32 v183, 1.0, v183
	v_rcp_f32_e32 v183, v183
	v_lshlrev_b32_e32 v36, 16, v43
	v_mul_f32_e32 v210, v169, v175
	v_mul_f32_e32 v169, v60, v228
	v_mul_f32_e32 v175, v70, v247
	v_mul_f32_e32 v211, v182, v183
	v_fmac_f32_e32 v169, v54, v218
	v_fmac_f32_e32 v175, v62, v245
	v_mul_f32_e32 v182, v61, v244
	v_mul_f32_e32 v183, v71, v248
	v_add_f32_e32 v169, v169, v175
	v_fmac_f32_e32 v182, v55, v219
	v_fmac_f32_e32 v183, v63, v246
	v_mul_f32_e32 v175, 0xbfb8aa3b, v169
	v_add_f32_e32 v182, v182, v183
	v_exp_f32_e32 v175, v175
	v_mul_f32_e32 v183, 0xbfb8aa3b, v182
	v_exp_f32_e32 v183, v183
	v_and_b32_e32 v37, 0xffff0000, v43
	v_lshlrev_b32_e32 v42, 16, v185
	v_and_b32_e32 v43, 0xffff0000, v185
	s_lshl_b32 s10, s90, 3
	v_lshl_add_u32 v185, v102, 2, s64
	s_mul_i32 s11, s90, 0x880
	v_add_u32_e32 v236, s11, v185
	s_or_b32 s11, s10, 1
	v_add_u32_e32 v203, 0x1fc00, v185
	s_mul_i32 s65, s11, 0x110
	v_add_f32_e32 v175, 1.0, v175
	v_lshlrev_b32_e32 v249, 16, v204
	v_and_b32_e32 v250, 0xffff0000, v204
	v_add_u32_e32 v204, s65, v185
	v_lshl_add_u32 v231, s11, 8, v203
	v_and_or_b32 v185, s11, 57, v201
	s_or_b32 s11, s10, 2
	v_rcp_f32_e32 v175, v175
	v_add_f32_e32 v183, 1.0, v183
	v_lshlrev_b32_e32 v232, 2, v185
	v_lshl_add_u32 v226, s11, 8, v203
	v_and_or_b32 v185, s11, 58, v201
	s_or_b32 s11, s10, 3
	v_rcp_f32_e32 v183, v183
	v_lshlrev_b32_e32 v227, 2, v185
	v_lshl_add_u32 v222, s11, 8, v203
	v_and_or_b32 v185, s11, 59, v201
	s_or_b32 s11, s10, 4
	v_lshlrev_b32_e32 v176, 16, v153
	v_lshl_add_u32 v216, s11, 8, v203
	v_and_or_b32 v184, s11, 60, v201
	s_or_b32 s11, s10, 5
	v_lshlrev_b32_e32 v160, 16, v38
	v_and_b32_e32 v161, 0xffff0000, v38
	v_lshlrev_b32_e32 v46, 16, v39
	v_and_b32_e32 v162, 0xffff0000, v39
	v_lshlrev_b32_e32 v179, 16, v173
	v_lshlrev_b32_e32 v38, 16, v181
	v_and_b32_e32 v39, 0xffff0000, v181
	v_lshlrev_b32_e32 v181, 16, v205
	v_and_b32_e32 v171, 0xffff0000, v205
	v_lshlrev_b32_e32 v217, 2, v184
	v_lshl_add_u32 v212, s11, 8, v203
	v_and_or_b32 v184, s11, 61, v201
	v_mul_f32_e32 v205, v169, v175
	s_or_b32 s11, s10, 6
	v_mov_b32_e32 v175, v176
	v_lshlrev_b32_e32 v177, 16, v156
	v_and_b32_e32 v157, 0xffff0000, v156
	v_and_b32_e32 v156, 0xffff0000, v153
	v_lshlrev_b32_e32 v223, 2, v185
	v_lshlrev_b32_e32 v213, 2, v184
	v_mul_f32_e32 v207, v182, v183
	v_and_or_b32 v169, s11, 62, v201
	v_pk_mul_f32 v[182:183], v[58:59], v[174:175]
	v_pk_mov_b32 v[184:185], v[46:47], v[178:179] op_sel:[1,0]
	v_lshlrev_b32_e32 v209, 2, v169
	v_pk_fma_f32 v[182:183], v[74:75], v[46:47], v[182:183]
	v_pk_mul_f32 v[184:185], v[58:59], v[184:185]
	v_mov_b32_e32 v46, v47
	v_mov_b32_e32 v47, v177
	v_mov_b32_e32 v169, v156
	v_pk_fma_f32 v[174:175], v[74:75], v[174:175], v[184:185]
	v_mov_b32_e32 v184, v176
	v_mov_b32_e32 v185, v178
	v_pk_mul_f32 v[46:47], v[84:85], v[46:47]
	v_pk_mul_f32 v[240:241], v[68:69], v[168:169]
	v_lshlrev_b32_e32 v164, 16, v155
	v_and_b32_e32 v165, 0xffff0000, v155
	v_and_b32_e32 v155, 0xffff0000, v173
	v_lshlrev_b32_e32 v173, 16, v186
	v_and_b32_e32 v153, 0xffff0000, v186
	v_and_or_b32 v186, s10, 56, v201
	v_pk_fma_f32 v[184:185], v[82:83], v[184:185], v[46:47]
	v_pk_mul_f32 v[46:47], v[58:59], v[178:179]
	v_pk_fma_f32 v[240:241], v[52:53], v[162:163], v[240:241]
	v_lshlrev_b32_e32 v44, 16, v187
	v_and_b32_e32 v45, 0xffff0000, v187
	v_lshlrev_b32_e32 v238, 2, v186
	v_pk_fma_f32 v[186:187], v[74:75], v[176:177], v[46:47]
	v_pk_mov_b32 v[46:47], v[176:177], v[172:173] op_sel:[1,0]
	v_mov_b32_e32 v242, v182
	v_mov_b32_e32 v243, v240
	v_mov_b32_e32 v240, v183
	v_pk_mul_f32 v[176:177], v[58:59], v[46:47]
	v_pk_mov_b32 v[218:219], v[178:179], v[180:181] op_sel:[1,0]
	v_pk_add_f32 v[182:183], v[242:243], v[240:241]
	v_pk_fma_f32 v[176:177], v[74:75], v[178:179], v[176:177]
	v_pk_mul_f32 v[218:219], v[58:59], v[218:219]
	v_mov_b32_e32 v178, v179
	v_mov_b32_e32 v179, v173
	v_mul_f32_e32 v233, 0xbfb8aa3b, v182
	v_pk_fma_f32 v[218:219], v[74:75], v[46:47], v[218:219]
	v_mov_b32_e32 v46, v172
	v_mov_b32_e32 v47, v180
	v_exp_f32_e32 v233, v233
	v_mul_f32_e32 v239, 0xbfb8aa3b, v183
	v_pk_mul_f32 v[178:179], v[84:85], v[178:179]
	v_exp_f32_e32 v239, v239
	v_pk_fma_f32 v[178:179], v[82:83], v[46:47], v[178:179]
	v_pk_mul_f32 v[46:47], v[58:59], v[180:181]
	v_pk_mov_b32 v[180:181], v[162:163], v[154:155] op_sel:[1,0]
	v_add_f32_e32 v233, 1.0, v233
	v_pk_mul_f32 v[180:181], v[68:69], v[180:181]
	v_rcp_f32_e32 v240, v233
	v_pk_fma_f32 v[168:169], v[52:53], v[168:169], v[180:181]
	v_mov_b32_e32 v180, v174
	v_mov_b32_e32 v181, v168
	v_mov_b32_e32 v168, v175
	v_add_f32_e32 v233, 1.0, v239
	v_pk_add_f32 v[168:169], v[180:181], v[168:169]
	v_rcp_f32_e32 v241, v233
	v_mul_f32_e32 v162, 0xbfb8aa3b, v168
	v_exp_f32_e32 v162, v162
	v_mul_f32_e32 v174, 0xbfb8aa3b, v169
	v_exp_f32_e32 v174, v174
	v_pk_mul_f32 v[182:183], v[182:183], v[240:241]
	v_pk_fma_f32 v[46:47], v[74:75], v[172:173], v[46:47]
	v_pk_mul_f32 v[172:173], v[182:183], v[182:183]
	v_add_f32_e32 v162, 1.0, v162
	v_add_f32_e32 v251, v172, v173
	v_rcp_f32_e32 v172, v162
	v_add_f32_e32 v162, 1.0, v174
	v_rcp_f32_e32 v173, v162
	v_mov_b32_e32 v162, v163
	v_mov_b32_e32 v163, v157
	v_mov_b32_e32 v174, v156
	v_mov_b32_e32 v175, v154
	v_pk_mul_f32 v[162:163], v[78:79], v[162:163]
	v_pk_mul_f32 v[180:181], v[168:169], v[172:173]
	v_pk_fma_f32 v[162:163], v[80:81], v[174:175], v[162:163]
	v_mov_b32_e32 v174, v184
	v_mov_b32_e32 v175, v162
	v_mov_b32_e32 v162, v185
	v_pk_add_f32 v[162:163], v[174:175], v[162:163]
	v_pk_mul_f32 v[172:173], v[68:69], v[154:155]
	v_mul_f32_e32 v174, 0xbfb8aa3b, v162
	v_mul_f32_e32 v175, 0xbfb8aa3b, v163
	v_exp_f32_e32 v174, v174
	v_exp_f32_e32 v175, v175
	v_pk_fma_f32 v[172:173], v[52:53], v[156:157], v[172:173]
	v_pk_mov_b32 v[156:157], v[156:157], v[152:153] op_sel:[1,0]
	v_add_f32_e32 v168, 1.0, v174
	v_add_f32_e32 v169, 1.0, v175
	v_mov_b32_e32 v174, v186
	v_mov_b32_e32 v175, v172
	v_mov_b32_e32 v172, v187
	v_pk_add_f32 v[174:175], v[174:175], v[172:173]
	v_rcp_f32_e32 v168, v168
	v_mul_f32_e32 v172, 0xbfb8aa3b, v174
	v_exp_f32_e32 v172, v172
	v_mul_f32_e32 v173, 0xbfb8aa3b, v175
	v_exp_f32_e32 v173, v173
	v_rcp_f32_e32 v169, v169
	v_add_f32_e32 v172, 1.0, v172
	v_rcp_f32_e32 v184, v172
	v_add_f32_e32 v172, 1.0, v173
	v_rcp_f32_e32 v185, v172
	v_pk_mul_f32 v[172:173], v[162:163], v[168:169]
	v_pk_mul_f32 v[240:241], v[56:57], v[158:159]
	v_pk_mul_f32 v[162:163], v[172:173], v[172:173]
	v_pk_mul_f32 v[168:169], v[174:175], v[184:185]
	v_add_f32_e32 v253, v162, v163
	v_pk_mul_f32 v[162:163], v[68:69], v[156:157]
	v_mov_b32_e32 v184, v176
	v_pk_fma_f32 v[162:163], v[52:53], v[154:155], v[162:163]
	v_pk_mul_f32 v[174:175], v[168:169], v[168:169]
	v_mov_b32_e32 v185, v162
	v_mov_b32_e32 v162, v177
	v_pk_add_f32 v[162:163], v[184:185], v[162:163]
	v_add_f32_e32 v254, v174, v175
	v_mul_f32_e32 v176, 0xbfb8aa3b, v162
	v_mul_f32_e32 v177, 0xbfb8aa3b, v163
	v_exp_f32_e32 v176, v176
	v_exp_f32_e32 v177, v177
	v_pk_mul_f32 v[242:243], v[48:49], v[32:33]
	v_pk_fma_f32 v[240:241], v[50:51], v[36:37], v[240:241]
	v_add_f32_e32 v174, 1.0, v176
	v_add_f32_e32 v175, 1.0, v177
	v_pk_mov_b32 v[176:177], v[154:155], v[170:171] op_sel:[1,0]
	v_rcp_f32_e32 v174, v174
	v_pk_mul_f32 v[176:177], v[68:69], v[176:177]
	v_rcp_f32_e32 v175, v175
	v_pk_fma_f32 v[156:157], v[52:53], v[156:157], v[176:177]
	v_mov_b32_e32 v176, v218
	v_mov_b32_e32 v177, v156
	v_mov_b32_e32 v156, v219
	v_pk_add_f32 v[156:157], v[176:177], v[156:157]
	v_mov_b32_e32 v177, v153
	v_mul_f32_e32 v176, 0xbfb8aa3b, v157
	v_exp_f32_e32 v176, v176
	v_pk_fma_f32 v[160:161], v[72:73], v[160:161], v[242:243]
	v_pk_mul_f32 v[162:163], v[162:163], v[174:175]
	v_mov_b32_e32 v174, v152
	v_add_f32_e32 v184, 1.0, v176
	v_mov_b32_e32 v176, v155
	v_mov_b32_e32 v175, v170
	v_pk_mul_f32 v[176:177], v[78:79], v[176:177]
	v_pk_add_f32 v[160:161], v[160:161], v[240:241]
	v_pk_fma_f32 v[174:175], v[80:81], v[174:175], v[176:177]
	v_mul_f32_e32 v240, 0xbfb8aa3b, v160
	v_mul_f32_e32 v241, 0xbfb8aa3b, v161
	v_mov_b32_e32 v176, v178
	v_mov_b32_e32 v177, v174
	v_mov_b32_e32 v174, v179
	v_exp_f32_e32 v240, v240
	v_exp_f32_e32 v241, v241
	v_pk_add_f32 v[174:175], v[176:177], v[174:175]
	v_mul_f32_e32 v154, 0xbfb8aa3b, v156
	v_mul_f32_e32 v155, 0xbfb8aa3b, v174
	v_exp_f32_e32 v176, v155
	v_mul_f32_e32 v155, 0xbfb8aa3b, v175
	v_exp_f32_e32 v154, v154
	v_exp_f32_e32 v177, v155
	v_add_f32_e32 v240, 1.0, v240
	v_add_f32_e32 v241, 1.0, v241
	v_rcp_f32_e32 v240, v240
	v_rcp_f32_e32 v241, v241
	v_add_f32_e32 v154, 1.0, v154
	v_add_f32_e32 v176, 1.0, v176
	v_add_f32_e32 v177, 1.0, v177
	v_rcp_f32_e32 v154, v154
	v_rcp_f32_e32 v155, v184
	v_rcp_f32_e32 v176, v176
	v_rcp_f32_e32 v177, v177
	v_pk_mul_f32 v[160:161], v[160:161], v[240:241]
	v_pk_mul_f32 v[178:179], v[162:163], v[162:163]
	v_pk_mul_f32 v[240:241], v[160:161], v[160:161]
	v_pk_mul_f32 v[156:157], v[156:157], v[154:155]
	v_add_f32_e32 v240, v240, v241
	v_pk_mul_f32 v[154:155], v[174:175], v[176:177]
	v_add_f32_e32 v239, v178, v179
	v_add_f32_dpp v240, v240, v240 row_ror:8 row_mask:0xf bank_mask:0xf bound_ctrl:1
	v_mul_f32_e32 v176, v60, v245
	v_mul_f32_e32 v177, v70, v249
	v_mul_f32_e32 v178, v61, v246
	v_mul_f32_e32 v179, v71, v250
	v_add_f32_dpp v240, v240, v240 row_ror:4 row_mask:0xf bank_mask:0xf bound_ctrl:1
	v_fmac_f32_e32 v176, v54, v228
	v_fmac_f32_e32 v177, v62, v247
	v_fmac_f32_e32 v178, v55, v244
	v_fmac_f32_e32 v179, v63, v248
	v_add_f32_dpp v240, v240, v240 row_ror:2 row_mask:0xf bank_mask:0xf bound_ctrl:1
	v_add_f32_e32 v176, v176, v177
	v_add_f32_e32 v178, v178, v179
	v_add_f32_dpp v240, v240, v240 row_ror:1 row_mask:0xf bank_mask:0xf bound_ctrl:1
	v_mul_f32_e32 v177, 0xbfb8aa3b, v176
	v_mul_f32_e32 v179, 0xbfb8aa3b, v178
	v_readlane_b32 s66, v240, 16
	v_readlane_b32 s67, v240, 48
	v_lshl_add_u32 v208, s11, 8, v203
	v_exp_f32_e32 v177, v177
	v_exp_f32_e32 v179, v179
	s_or_b32 s65, s10, 7
	v_readlane_b32 s10, v240, 0
	v_readlane_b32 s11, v240, 32
	v_mov_b32_e32 v240, s66
	v_mov_b32_e32 v241, s67
	v_pk_add_f32 v[240:241], s[10:11], v[240:241]
	v_pk_mul_f32 v[174:175], v[154:155], v[154:155]
	v_add_f32_e32 v240, v240, v241
	v_add_f32_e32 v240, 0x358637bd, v240
	v_add_f32_e32 v228, v174, v175
	v_add_f32_e32 v174, 1.0, v177
	v_add_f32_e32 v175, 1.0, v179
	v_mul_f32_e32 v241, 0x4b800000, v240
	v_cmp_gt_f32_e32 vcc, s81, v240
	v_rcp_f32_e32 v174, v174
	v_rcp_f32_e32 v175, v175
	v_cndmask_b32_e32 v240, v240, v241, vcc
	v_rsq_f32_e32 v240, v240
	v_pk_mul_f32 v[184:185], v[156:157], v[156:157]
	v_pk_mul_f32 v[242:243], v[48:49], v[158:159]
	v_add_f32_e32 v233, v184, v185
	v_mul_f32_e32 v218, v176, v174
	v_mul_f32_e32 v219, v178, v175
	v_pk_mul_f32 v[174:175], v[48:49], v[40:41]
	v_pk_mul_f32 v[184:185], v[56:57], v[40:41]
	v_pk_fma_f32 v[242:243], v[72:73], v[36:37], v[242:243]
	v_pk_mul_f32 v[36:37], v[48:49], v[36:37]
	v_pk_mul_f32 v[186:187], v[180:181], v[180:181]
	v_pk_fma_f32 v[174:175], v[72:73], v[166:167], v[174:175]
	v_pk_mul_f32 v[178:179], v[48:49], v[166:167]
	v_pk_fma_f32 v[184:185], v[50:51], v[166:167], v[184:185]
	v_pk_mul_f32 v[166:167], v[56:57], v[166:167]
	v_pk_fma_f32 v[32:33], v[72:73], v[32:33], v[36:37]
	v_mul_f32_e32 v36, 0x45800000, v240
	v_add_f32_e32 v252, v186, v187
	v_pk_fma_f32 v[178:179], v[72:73], v[164:165], v[178:179]
	v_pk_mul_f32 v[186:187], v[48:49], v[164:165]
	v_pk_fma_f32 v[166:167], v[50:51], v[164:165], v[166:167]
	v_pk_mul_f32 v[164:165], v[56:57], v[164:165]
	v_cndmask_b32_e32 v36, v240, v36, vcc
	v_pk_fma_f32 v[186:187], v[72:73], v[158:159], v[186:187]
	v_pk_fma_f32 v[158:159], v[50:51], v[158:159], v[164:165]
	v_mul_f32_e32 v164, 0x3db504f3, v36
	v_add_f32_dpp v36, v251, v251 row_ror:8 row_mask:0xf bank_mask:0xf bound_ctrl:1
	v_pk_add_f32 v[32:33], v[32:33], v[158:159]
	ds_bpermute_b32 v158, v238, v202
	v_add_f32_dpp v36, v36, v36 row_ror:4 row_mask:0xf bank_mask:0xf bound_ctrl:1
	v_lshl_add_u32 v237, s90, 11, v203
	v_pk_mul_f32 v[176:177], v[56:57], v[34:35]
	v_add_f32_dpp v36, v36, v36 row_ror:2 row_mask:0xf bank_mask:0xf bound_ctrl:1
	v_pk_fma_f32 v[176:177], v[50:51], v[40:41], v[176:177]
	v_pk_mul_f32 v[170:171], v[68:69], v[170:171]
	v_add_f32_dpp v36, v36, v36 row_ror:1 row_mask:0xf bank_mask:0xf bound_ctrl:1
	v_pk_fma_f32 v[152:153], v[52:53], v[152:153], v[170:171]
	v_readlane_b32 s66, v36, 16
	v_readlane_b32 s67, v36, 48
	v_readlane_b32 s10, v36, 0
	v_readlane_b32 s11, v36, 32
	v_mov_b32_e32 v36, s66
	v_mov_b32_e32 v37, s67
	v_pk_add_f32 v[36:37], s[10:11], v[36:37]
	v_pk_mul_f32 v[170:171], v[56:57], v[38:39]
	v_add_f32_e32 v36, v36, v37
	v_add_f32_e32 v36, 0x358637bd, v36
	v_mul_f32_e32 v37, 0x4b800000, v36
	v_cmp_gt_f32_e32 vcc, s81, v36
	v_pk_fma_f32 v[170:171], v[50:51], v[34:35], v[170:171]
	s_nop 0
	v_cndmask_b32_e32 v36, v36, v37, vcc
	v_rsq_f32_e32 v36, v36
	v_mul_f32_e32 v37, v160, v164
	v_mul_f32_e32 v160, v161, v164
	v_cvt_pk_bf16_f32 v37, v37, v160
	v_mul_f32_e32 v160, 0x45800000, v36
	v_cndmask_b32_e32 v36, v36, v160, vcc
	v_mul_f32_e32 v160, v182, v36
	v_mul_f32_e32 v161, v183, v36
	v_cvt_pk_bf16_f32 v36, v160, v161
	ds_write2st64_b32 v236, v37, v36 offset1:68
	v_mul_f32_e32 v36, 0xbfb8aa3b, v32
	v_mul_f32_e32 v37, 0xbfb8aa3b, v33
	v_exp_f32_e32 v36, v36
	v_exp_f32_e32 v37, v37
	v_cvt_pk_bf16_f32 v164, v234, v235
	s_waitcnt lgkmcnt(1)
	v_mul_f32_e32 v159, v160, v158
	v_add_f32_e32 v36, 1.0, v36
	v_add_f32_e32 v37, 1.0, v37
	v_rcp_f32_e32 v36, v36
	v_rcp_f32_e32 v37, v37
	v_mul_f32_e32 v158, v161, v158
	ds_write_b32 v237, v164
	v_pk_mul_f32 v[32:33], v[32:33], v[36:37]
	s_nop 0
	v_pk_mul_f32 v[36:37], v[32:33], v[32:33]
	s_nop 0
	v_add_f32_e32 v36, v36, v37
	s_nop 1
	v_add_f32_dpp v36, v36, v36 row_ror:8 row_mask:0xf bank_mask:0xf bound_ctrl:1
	s_nop 1
	v_add_f32_dpp v36, v36, v36 row_ror:4 row_mask:0xf bank_mask:0xf bound_ctrl:1
	s_nop 1
	v_add_f32_dpp v36, v36, v36 row_ror:2 row_mask:0xf bank_mask:0xf bound_ctrl:1
	s_nop 1
	v_add_f32_dpp v36, v36, v36 row_ror:1 row_mask:0xf bank_mask:0xf bound_ctrl:1
	s_nop 0
	v_readlane_b32 s66, v36, 16
	v_readlane_b32 s67, v36, 48
	v_readlane_b32 s10, v36, 0
	v_readlane_b32 s11, v36, 32
	v_mov_b32_e32 v36, s66
	v_mov_b32_e32 v37, s67
	v_pk_add_f32 v[36:37], s[10:11], v[36:37]
	s_nop 0
	v_add_f32_e32 v36, v36, v37
	v_add_f32_e32 v36, 0x358637bd, v36
	v_mul_f32_e32 v37, 0x4b800000, v36
	v_cmp_gt_f32_e32 vcc, s81, v36
	s_nop 1
	v_cndmask_b32_e32 v36, v36, v37, vcc
	v_rsq_f32_e32 v36, v36
	v_cvt_pk_bf16_f32 v37, v159, v158
	s_nop 0
	v_and_b32_e32 v164, 0xffff, v37
	v_lshrrev_b32_e32 v165, 16, v37
	v_mul_f32_e32 v37, 0x45800000, v36
	v_cndmask_b32_e32 v36, v36, v37, vcc
	v_mul_f32_e32 v158, 0x3db504f3, v36
	v_mul_f32_e32 v32, v32, v158
	v_add_f32_dpp v36, v252, v252 row_ror:8 row_mask:0xf bank_mask:0xf bound_ctrl:1
	v_mul_f32_e32 v33, v33, v158
	v_cvt_pk_bf16_f32 v158, v229, v230
	ds_write_b32 v231, v158
	v_add_f32_dpp v36, v36, v36 row_ror:4 row_mask:0xf bank_mask:0xf bound_ctrl:1
	v_pk_add_f32 v[158:159], v[242:243], v[166:167]
	s_nop 0
	v_add_f32_dpp v36, v36, v36 row_ror:2 row_mask:0xf bank_mask:0xf bound_ctrl:1
	s_nop 1
	v_add_f32_dpp v36, v36, v36 row_ror:1 row_mask:0xf bank_mask:0xf bound_ctrl:1
	s_nop 0
	v_readlane_b32 s66, v36, 16
	v_readlane_b32 s67, v36, 48
	v_readlane_b32 s10, v36, 0
	v_readlane_b32 s11, v36, 32
	v_mov_b32_e32 v36, s66
	v_mov_b32_e32 v37, s67
	v_pk_add_f32 v[36:37], s[10:11], v[36:37]
	s_nop 0
	v_add_f32_e32 v36, v36, v37
	v_add_f32_e32 v36, 0x358637bd, v36
	v_mul_f32_e32 v37, 0x4b800000, v36
	v_cmp_gt_f32_e32 vcc, s81, v36
	s_nop 1
	v_cndmask_b32_e32 v36, v36, v37, vcc
	v_rsq_f32_e32 v36, v36
	v_cvt_pk_bf16_f32 v37, v32, v33
	s_nop 0
	v_mul_f32_e32 v32, 0x45800000, v36
	v_cndmask_b32_e32 v32, v36, v32, vcc
	ds_bpermute_b32 v36, v232, v202
	v_mul_f32_e32 v33, v180, v32
	v_mul_f32_e32 v32, v181, v32
	v_cvt_pk_bf16_f32 v180, v33, v32
	s_waitcnt lgkmcnt(0)
	v_mul_f32_e32 v32, v32, v36
	v_mul_f32_e32 v33, v33, v36
	v_cvt_pk_bf16_f32 v181, v33, v32
	s_nop 0
	v_add_f32_dpp v32, v253, v253 row_ror:8 row_mask:0xf bank_mask:0xf bound_ctrl:1
	v_mul_f32_e32 v36, 0xbfb8aa3b, v159
	v_exp_f32_e32 v36, v36
	v_add_f32_dpp v32, v32, v32 row_ror:4 row_mask:0xf bank_mask:0xf bound_ctrl:1
	s_nop 1
	v_add_f32_dpp v32, v32, v32 row_ror:2 row_mask:0xf bank_mask:0xf bound_ctrl:1
	s_nop 1
	v_add_f32_dpp v32, v32, v32 row_ror:1 row_mask:0xf bank_mask:0xf bound_ctrl:1
	s_nop 0
	v_readlane_b32 s66, v32, 16
	v_readlane_b32 s67, v32, 48
	v_readlane_b32 s10, v32, 0
	v_readlane_b32 s11, v32, 32
	v_mov_b32_e32 v32, s66
	v_mov_b32_e32 v33, s67
	v_pk_add_f32 v[32:33], s[10:11], v[32:33]
	s_nop 0
	v_add_f32_e32 v32, v32, v33
	v_add_f32_e32 v32, 0x358637bd, v32
	v_mul_f32_e32 v33, 0x4b800000, v32
	v_cmp_gt_f32_e32 vcc, s81, v32
	s_nop 1
	v_cndmask_b32_e32 v32, v32, v33, vcc
	v_mul_f32_e32 v33, 0xbfb8aa3b, v158
	v_exp_f32_e32 v33, v33
	v_rsq_f32_e32 v166, v32
	v_add_f32_e32 v32, 1.0, v33
	v_rcp_f32_e32 v160, v32
	v_add_f32_e32 v32, 1.0, v36
	v_rcp_f32_e32 v161, v32
	v_lshl_or_b32 v36, v181, 16, v164
	v_mul_f32_e32 v33, 0x45800000, v166
	v_cndmask_b32_e32 v33, v166, v33, vcc
	v_pk_mul_f32 v[158:159], v[158:159], v[160:161]
	v_and_or_b32 v32, v181, s79, v165
	v_pk_mul_f32 v[160:161], v[158:159], v[158:159]
	s_nop 0
	v_add_f32_e32 v160, v160, v161
	s_nop 1
	v_add_f32_dpp v160, v160, v160 row_ror:8 row_mask:0xf bank_mask:0xf bound_ctrl:1
	s_nop 1
	v_add_f32_dpp v160, v160, v160 row_ror:4 row_mask:0xf bank_mask:0xf bound_ctrl:1
	s_nop 1
	v_add_f32_dpp v160, v160, v160 row_ror:2 row_mask:0xf bank_mask:0xf bound_ctrl:1
	s_nop 1
	v_add_f32_dpp v160, v160, v160 row_ror:1 row_mask:0xf bank_mask:0xf bound_ctrl:1
	s_nop 0
	v_readlane_b32 s66, v160, 16
	v_readlane_b32 s67, v160, 48
	v_readlane_b32 s10, v160, 0
	v_readlane_b32 s11, v160, 32
	v_mov_b32_e32 v160, s66
	v_mov_b32_e32 v161, s67
	v_pk_add_f32 v[160:161], s[10:11], v[160:161]
	s_nop 0
	v_add_f32_e32 v160, v160, v161
	v_add_f32_e32 v160, 0x358637bd, v160
	v_mul_f32_e32 v161, 0x4b800000, v160
	v_cmp_gt_f32_e64 s[10:11], s81, v160
	s_nop 1
	v_cndmask_b32_e64 v160, v160, v161, s[10:11]
	v_rsq_f32_e32 v160, v160
	v_mul_f32_e32 v161, v172, v33
	v_mul_f32_e32 v33, v173, v33
	v_add_u32_e32 v172, 0x4400, v204
	v_mul_f32_e32 v164, 0x45800000, v160
	v_cndmask_b32_e64 v160, v160, v164, s[10:11]
	v_mul_f32_e32 v160, 0x3db504f3, v160
	v_mul_f32_e32 v158, v158, v160
	v_mul_f32_e32 v159, v159, v160
	v_cvt_pk_bf16_f32 v158, v158, v159
	ds_write2_b32 v204, v37, v158 offset1:68
	ds_bpermute_b32 v158, v227, v202
	v_cvt_pk_bf16_f32 v37, v161, v33
	ds_write2_b32 v172, v180, v37 offset1:68
	v_cvt_pk_bf16_f32 v37, v224, v225
	ds_write_b32 v226, v37
	s_waitcnt lgkmcnt(2)
	v_mul_f32_e32 v37, v161, v158
	v_mul_f32_e32 v33, v33, v158
	v_cvt_pk_bf16_f32 v33, v37, v33
	s_nop 0
	v_add_f32_dpp v37, v254, v254 row_ror:8 row_mask:0xf bank_mask:0xf bound_ctrl:1
	v_and_b32_e32 v164, 0xffff, v33
	v_lshrrev_b32_e32 v33, 16, v33
	v_add_f32_dpp v37, v37, v37 row_ror:4 row_mask:0xf bank_mask:0xf bound_ctrl:1
	s_nop 1
	v_add_f32_dpp v37, v37, v37 row_ror:2 row_mask:0xf bank_mask:0xf bound_ctrl:1
	s_nop 1
	v_add_f32_dpp v37, v37, v37 row_ror:1 row_mask:0xf bank_mask:0xf bound_ctrl:1
	s_nop 0
	v_readlane_b32 s66, v37, 16
	v_readlane_b32 s67, v37, 48
	v_readlane_b32 s10, v37, 0
	v_readlane_b32 s11, v37, 32
	v_mov_b32_e32 v158, s66
	v_mov_b32_e32 v159, s67
	v_pk_add_f32 v[158:159], s[10:11], v[158:159]
	s_nop 0
	v_add_f32_e32 v37, v158, v159
	v_add_f32_e32 v37, 0x358637bd, v37
	v_mul_f32_e32 v158, 0x4b800000, v37
	v_cmp_gt_f32_e32 vcc, s81, v37
	s_nop 1
	v_cndmask_b32_e32 v37, v37, v158, vcc
	v_pk_add_f32 v[158:159], v[186:187], v[184:185]
	v_rsq_f32_e32 v37, v37
	v_mul_f32_e32 v160, 0xbfb8aa3b, v158
	v_mul_f32_e32 v161, 0xbfb8aa3b, v159
	v_exp_f32_e32 v160, v160
	v_exp_f32_e32 v161, v161
	v_mul_f32_e32 v165, 0x45800000, v37
	v_cndmask_b32_e32 v37, v37, v165, vcc
	v_add_f32_e32 v160, 1.0, v160
	v_add_f32_e32 v161, 1.0, v161
	v_rcp_f32_e32 v160, v160
	v_rcp_f32_e32 v161, v161
	s_nop 0
	v_pk_mul_f32 v[158:159], v[158:159], v[160:161]
	s_nop 0
	v_pk_mul_f32 v[160:161], v[158:159], v[158:159]
	s_nop 0
	v_add_f32_e32 v160, v160, v161
	s_nop 1
	v_add_f32_dpp v160, v160, v160 row_ror:8 row_mask:0xf bank_mask:0xf bound_ctrl:1
	s_nop 1
	v_add_f32_dpp v160, v160, v160 row_ror:4 row_mask:0xf bank_mask:0xf bound_ctrl:1
	s_nop 1
	v_add_f32_dpp v160, v160, v160 row_ror:2 row_mask:0xf bank_mask:0xf bound_ctrl:1
	s_nop 1
	v_add_f32_dpp v160, v160, v160 row_ror:1 row_mask:0xf bank_mask:0xf bound_ctrl:1
	s_nop 0
	v_readlane_b32 s66, v160, 16
	v_readlane_b32 s67, v160, 48
	v_readlane_b32 s10, v160, 0
	v_readlane_b32 s11, v160, 32
	v_mov_b32_e32 v160, s66
	v_mov_b32_e32 v161, s67
	v_pk_add_f32 v[160:161], s[10:11], v[160:161]
	s_nop 0
	v_add_f32_e32 v160, v160, v161
	v_add_f32_e32 v160, 0x358637bd, v160
	v_mul_f32_e32 v161, 0x4b800000, v160
	v_cmp_gt_f32_e64 s[10:11], s81, v160
	s_nop 1
	v_cndmask_b32_e64 v160, v160, v161, s[10:11]
	v_rsq_f32_e32 v160, v160
	v_mul_f32_e32 v161, v168, v37
	v_mul_f32_e32 v37, v169, v37
	v_cvt_pk_bf16_f32 v169, v161, v37
	v_mul_f32_e32 v165, 0x45800000, v160
	v_cndmask_b32_e64 v160, v160, v165, s[10:11]
	v_mul_f32_e32 v160, 0x3db504f3, v160
	v_mul_f32_e32 v158, v158, v160
	v_mul_f32_e32 v159, v159, v160
	ds_bpermute_b32 v160, v223, v202
	v_cvt_pk_bf16_f32 v168, v158, v159
	v_cvt_pk_bf16_f32 v158, v220, v221
	ds_write_b32 v222, v158
	s_waitcnt lgkmcnt(1)
	v_mul_f32_e32 v158, v161, v160
	v_mul_f32_e32 v37, v37, v160
	v_cvt_pk_bf16_f32 v160, v158, v37
	v_pk_add_f32 v[158:159], v[178:179], v[176:177]
	v_lshl_or_b32 v37, v160, 16, v164
	v_mul_f32_e32 v161, 0xbfb8aa3b, v158
	v_mul_f32_e32 v164, 0xbfb8aa3b, v159
	v_exp_f32_e32 v161, v161
	v_exp_f32_e32 v164, v164
	v_and_or_b32 v33, v160, s79, v33
	v_add_f32_e32 v160, 1.0, v161
	v_add_f32_e32 v161, 1.0, v164
	v_pk_add_f32 v[164:165], v[174:175], v[170:171]
	v_rcp_f32_e32 v160, v160
	v_mul_f32_e32 v166, 0xbfb8aa3b, v164
	v_mul_f32_e32 v167, 0xbfb8aa3b, v165
	v_exp_f32_e32 v166, v166
	v_exp_f32_e32 v167, v167
	v_rcp_f32_e32 v161, v161
	v_add_f32_e32 v166, 1.0, v166
	v_add_f32_e32 v167, 1.0, v167
	v_rcp_f32_e32 v166, v166
	v_rcp_f32_e32 v167, v167
	v_pk_mul_f32 v[158:159], v[158:159], v[160:161]
	s_nop 0
	v_pk_mul_f32 v[160:161], v[158:159], v[158:159]
	s_nop 0
	v_add_f32_e32 v170, v160, v161
	v_pk_mul_f32 v[160:161], v[164:165], v[166:167]
	v_pk_mul_f32 v[166:167], v[48:49], v[34:35]
	v_pk_mul_f32 v[164:165], v[160:161], v[160:161]
	v_pk_fma_f32 v[40:41], v[72:73], v[40:41], v[166:167]
	v_pk_mul_f32 v[166:167], v[56:57], v[42:43]
	v_add_f32_e32 v171, v164, v165
	v_pk_fma_f32 v[166:167], v[50:51], v[38:39], v[166:167]
	v_pk_mul_f32 v[38:39], v[48:49], v[38:39]
	v_pk_add_f32 v[40:41], v[40:41], v[166:167]
	v_pk_fma_f32 v[34:35], v[72:73], v[34:35], v[38:39]
	v_mul_f32_e32 v166, 0xbfb8aa3b, v40
	v_mul_f32_e32 v167, 0xbfb8aa3b, v41
	v_exp_f32_e32 v166, v166
	v_exp_f32_e32 v167, v167
	v_pk_mul_f32 v[38:39], v[56:57], v[44:45]
	v_add_f32_e32 v164, 1.0, v166
	v_add_f32_e32 v165, 1.0, v167
	v_rcp_f32_e32 v164, v164
	v_rcp_f32_e32 v165, v165
	v_pk_fma_f32 v[38:39], v[50:51], v[42:43], v[38:39]
	v_pk_mul_f32 v[42:43], v[40:41], v[164:165]
	v_add_f32_dpp v40, v170, v170 row_ror:8 row_mask:0xf bank_mask:0xf bound_ctrl:1
	v_pk_add_f32 v[34:35], v[34:35], v[38:39]
	s_nop 0
	v_add_f32_dpp v40, v40, v40 row_ror:4 row_mask:0xf bank_mask:0xf bound_ctrl:1
	v_mul_f32_e32 v38, 0xbfb8aa3b, v34
	v_mul_f32_e32 v39, 0xbfb8aa3b, v35
	v_add_f32_dpp v40, v40, v40 row_ror:2 row_mask:0xf bank_mask:0xf bound_ctrl:1
	v_exp_f32_e32 v38, v38
	v_exp_f32_e32 v39, v39
	v_add_f32_dpp v40, v40, v40 row_ror:1 row_mask:0xf bank_mask:0xf bound_ctrl:1
	v_add_f32_e32 v38, 1.0, v38
	v_readlane_b32 s66, v40, 16
	v_readlane_b32 s67, v40, 48
	v_readlane_b32 s10, v40, 0
	v_readlane_b32 s11, v40, 32
	v_mov_b32_e32 v40, s66
	v_mov_b32_e32 v41, s67
	v_pk_add_f32 v[40:41], s[10:11], v[40:41]
	v_add_f32_e32 v39, 1.0, v39
	v_add_f32_e32 v40, v40, v41
	v_add_f32_e32 v40, 0x358637bd, v40
	v_mul_f32_e32 v41, 0x4b800000, v40
	v_cmp_gt_f32_e32 vcc, s81, v40
	v_rcp_f32_e32 v38, v38
	v_rcp_f32_e32 v39, v39
	v_cndmask_b32_e32 v40, v40, v41, vcc
	v_rsq_f32_e32 v44, v40
	v_pk_mul_f32 v[40:41], v[42:43], v[42:43]
	s_nop 0
	v_add_f32_e32 v45, v40, v41
	v_pk_mul_f32 v[40:41], v[34:35], v[38:39]
	v_mul_f32_e32 v34, 0x45800000, v44
	v_cndmask_b32_e32 v34, v44, v34, vcc
	v_mul_f32_e32 v38, 0x3db504f3, v34
	v_mul_f32_e32 v39, v158, v38
	v_add_f32_dpp v34, v239, v239 row_ror:8 row_mask:0xf bank_mask:0xf bound_ctrl:1
	s_nop 1
	v_add_f32_dpp v34, v34, v34 row_ror:4 row_mask:0xf bank_mask:0xf bound_ctrl:1
	s_nop 1
	v_add_f32_dpp v34, v34, v34 row_ror:2 row_mask:0xf bank_mask:0xf bound_ctrl:1
	s_nop 1
	v_add_f32_dpp v34, v34, v34 row_ror:1 row_mask:0xf bank_mask:0xf bound_ctrl:1
	s_nop 0
	v_readlane_b32 s66, v34, 16
	v_readlane_b32 s67, v34, 48
	v_readlane_b32 s10, v34, 0
	v_readlane_b32 s11, v34, 32
	v_mov_b32_e32 v34, s66
	v_mov_b32_e32 v35, s67
	v_pk_add_f32 v[34:35], s[10:11], v[34:35]
	s_nop 0
	v_add_f32_e32 v34, v34, v35
	v_add_f32_e32 v34, 0x358637bd, v34
	v_mul_f32_e32 v35, 0x4b800000, v34
	v_cmp_gt_f32_e32 vcc, s81, v34
	s_nop 1
	v_cndmask_b32_e32 v34, v34, v35, vcc
	v_rsq_f32_e32 v34, v34
	v_mul_f32_e32 v35, v159, v38
	ds_bpermute_b32 v38, v217, v202
	v_cvt_pk_bf16_f32 v35, v39, v35
	ds_write2_b32 v204, v168, v35 offset0:136 offset1:204
	v_mul_f32_e32 v35, 0x45800000, v34
	v_cndmask_b32_e32 v34, v34, v35, vcc
	v_mul_f32_e32 v35, v162, v34
	v_mul_f32_e32 v34, v163, v34
	v_cvt_pk_bf16_f32 v39, v35, v34
	s_waitcnt lgkmcnt(1)
	v_mul_f32_e32 v34, v34, v38
	ds_write2_b32 v172, v169, v39 offset0:136 offset1:204
	v_cvt_pk_bf16_f32 v39, v214, v215
	v_mul_f32_e32 v35, v35, v38
	v_cvt_pk_bf16_f32 v34, v35, v34
	ds_write_b32 v216, v39
	v_and_b32_e32 v38, 0xffff, v34
	v_lshrrev_b32_e32 v39, 16, v34
	v_add_f32_dpp v34, v171, v171 row_ror:8 row_mask:0xf bank_mask:0xf bound_ctrl:1
	s_nop 1
	v_add_f32_dpp v34, v34, v34 row_ror:4 row_mask:0xf bank_mask:0xf bound_ctrl:1
	s_nop 1
	v_add_f32_dpp v34, v34, v34 row_ror:2 row_mask:0xf bank_mask:0xf bound_ctrl:1
	s_nop 1
	v_add_f32_dpp v34, v34, v34 row_ror:1 row_mask:0xf bank_mask:0xf bound_ctrl:1
	s_nop 0
	v_readlane_b32 s66, v34, 16
	v_readlane_b32 s67, v34, 48
	v_readlane_b32 s10, v34, 0
	v_readlane_b32 s11, v34, 32
	v_mov_b32_e32 v34, s66
	v_mov_b32_e32 v35, s67
	v_pk_add_f32 v[34:35], s[10:11], v[34:35]
	s_nop 0
	v_add_f32_e32 v44, v34, v35
	v_add_f32_dpp v34, v233, v233 row_ror:8 row_mask:0xf bank_mask:0xf bound_ctrl:1
	s_nop 1
	v_add_f32_dpp v34, v34, v34 row_ror:4 row_mask:0xf bank_mask:0xf bound_ctrl:1
	s_nop 1
	v_add_f32_dpp v34, v34, v34 row_ror:2 row_mask:0xf bank_mask:0xf bound_ctrl:1
	s_nop 1
	v_add_f32_dpp v34, v34, v34 row_ror:1 row_mask:0xf bank_mask:0xf bound_ctrl:1
	s_nop 0
	v_readlane_b32 s66, v34, 16
	v_readlane_b32 s67, v34, 48
	v_readlane_b32 s10, v34, 0
	v_readlane_b32 s11, v34, 32
	v_mov_b32_e32 v34, s66
	v_mov_b32_e32 v35, s67
	v_pk_add_f32 v[34:35], s[10:11], v[34:35]
	s_nop 0
	v_add_f32_e32 v34, v34, v35
	v_add_f32_e32 v35, 0x358637bd, v44
	v_mul_f32_e32 v44, 0x4b800000, v35
	v_cmp_gt_f32_e32 vcc, s81, v35
	v_add_f32_e32 v34, 0x358637bd, v34
	v_cmp_gt_f32_e64 s[10:11], s81, v34
	v_cndmask_b32_e32 v35, v35, v44, vcc
	v_rsq_f32_e32 v35, v35
	v_mul_f32_e32 v44, 0x4b800000, v34
	v_cndmask_b32_e64 v34, v34, v44, s[10:11]
	v_rsq_f32_e32 v34, v34
	v_mul_f32_e32 v44, 0x45800000, v35
	v_cndmask_b32_e32 v35, v35, v44, vcc
	v_mul_f32_e32 v35, 0x3db504f3, v35
	v_mul_f32_e32 v44, 0x45800000, v34
	v_cndmask_b32_e64 v34, v34, v44, s[10:11]
	v_mul_f32_e32 v44, v160, v35
	v_mul_f32_e32 v35, v161, v35
	v_cvt_pk_bf16_f32 v35, v44, v35
	ds_write_b32 v204, v35 offset:1088
	ds_bpermute_b32 v35, v213, v202
	v_mul_f32_e32 v156, v156, v34
	v_mul_f32_e32 v34, v157, v34
	v_cvt_pk_bf16_f32 v44, v156, v34
	ds_write_b32 v204, v44 offset:18496
	v_cvt_pk_bf16_f32 v44, v210, v211
	ds_write_b32 v212, v44
	s_waitcnt lgkmcnt(2)
	v_mul_f32_e32 v44, v156, v35
	v_mul_f32_e32 v34, v34, v35
	v_add_f32_dpp v35, v45, v45 row_ror:8 row_mask:0xf bank_mask:0xf bound_ctrl:1
	v_cvt_pk_bf16_f32 v34, v44, v34
	s_nop 0
	v_lshl_or_b32 v38, v34, 16, v38
	v_add_f32_dpp v35, v35, v35 row_ror:4 row_mask:0xf bank_mask:0xf bound_ctrl:1
	v_and_or_b32 v34, v34, s79, v39
	v_add_f32_dpp v39, v228, v228 row_ror:8 row_mask:0xf bank_mask:0xf bound_ctrl:1
	v_add_f32_dpp v35, v35, v35 row_ror:2 row_mask:0xf bank_mask:0xf bound_ctrl:1
	s_nop 0
	v_add_f32_dpp v39, v39, v39 row_ror:4 row_mask:0xf bank_mask:0xf bound_ctrl:1
	v_add_f32_dpp v35, v35, v35 row_ror:1 row_mask:0xf bank_mask:0xf bound_ctrl:1
	s_nop 0
	v_readlane_b32 s66, v35, 16
	v_readlane_b32 s67, v35, 48
	v_add_f32_dpp v39, v39, v39 row_ror:2 row_mask:0xf bank_mask:0xf bound_ctrl:1
	v_readlane_b32 s10, v35, 0
	v_readlane_b32 s11, v35, 32
	v_mov_b32_e32 v44, s66
	v_mov_b32_e32 v45, s67
	v_add_f32_dpp v39, v39, v39 row_ror:1 row_mask:0xf bank_mask:0xf bound_ctrl:1
	v_pk_add_f32 v[44:45], s[10:11], v[44:45]
	v_readlane_b32 s66, v39, 16
	v_readlane_b32 s67, v39, 48
	v_add_f32_e32 v35, v44, v45
	v_readlane_b32 s10, v39, 0
	v_readlane_b32 s11, v39, 32
	v_mov_b32_e32 v44, s66
	v_mov_b32_e32 v45, s67
	v_pk_add_f32 v[44:45], s[10:11], v[44:45]
	v_add_f32_e32 v35, 0x358637bd, v35
	v_add_f32_e32 v39, v44, v45
	v_mul_f32_e32 v44, 0x4b800000, v35
	v_cmp_gt_f32_e32 vcc, s81, v35
	v_add_f32_e32 v39, 0x358637bd, v39
	v_cmp_gt_f32_e64 s[10:11], s81, v39
	v_cndmask_b32_e32 v35, v35, v44, vcc
	v_rsq_f32_e32 v35, v35
	v_mul_f32_e32 v44, 0x4b800000, v39
	v_cndmask_b32_e64 v39, v39, v44, s[10:11]
	v_rsq_f32_e32 v39, v39
	v_mul_f32_e32 v44, 0x45800000, v35
	v_cndmask_b32_e32 v35, v35, v44, vcc
	v_mul_f32_e32 v35, 0x3db504f3, v35
	v_mul_f32_e32 v42, v42, v35
	v_mul_f32_e32 v35, v43, v35
	v_cvt_pk_bf16_f32 v35, v42, v35
	ds_write_b32 v204, v35 offset:1360
	ds_bpermute_b32 v35, v209, v202
	v_mul_f32_e32 v44, 0x45800000, v39
	v_cndmask_b32_e64 v39, v39, v44, s[10:11]
	v_mul_f32_e32 v43, v154, v39
	v_mul_f32_e32 v39, v155, v39
	v_cvt_pk_bf16_f32 v42, v43, v39
	ds_write_b32 v204, v42 offset:18768
	v_cvt_pk_bf16_f32 v42, v205, v207
	ds_write_b32 v208, v42
	s_waitcnt lgkmcnt(2)
	v_mul_f32_e32 v42, v43, v35
	v_mul_f32_e32 v35, v39, v35
	v_cvt_pk_bf16_f32 v35, v42, v35
	v_pk_mul_f32 v[42:43], v[40:41], v[40:41]
	v_and_b32_e32 v39, 0xffff, v35
	v_add_f32_e32 v42, v42, v43
	v_mov_b32_e32 v43, v152
	v_mov_b32_e32 v152, v47
	v_add_f32_dpp v42, v42, v42 row_ror:8 row_mask:0xf bank_mask:0xf bound_ctrl:1
	v_lshrrev_b32_e32 v35, 16, v35
	s_nop 0
	v_add_f32_dpp v42, v42, v42 row_ror:4 row_mask:0xf bank_mask:0xf bound_ctrl:1
	s_nop 1
	v_add_f32_dpp v42, v42, v42 row_ror:2 row_mask:0xf bank_mask:0xf bound_ctrl:1
	s_nop 1
	v_add_f32_dpp v42, v42, v42 row_ror:1 row_mask:0xf bank_mask:0xf bound_ctrl:1
	s_nop 0
	v_readlane_b32 s10, v42, 0
	v_readlane_b32 s66, v42, 16
	v_readlane_b32 s11, v42, 32
	v_readlane_b32 s67, v42, 48
	v_mov_b32_e32 v42, v46
	v_pk_add_f32 v[42:43], v[42:43], v[152:153]
	s_nop 0
	v_mul_f32_e32 v44, 0xbfb8aa3b, v42
	v_exp_f32_e32 v45, v44
	v_mul_f32_e32 v44, 0xbfb8aa3b, v43
	v_exp_f32_e32 v47, v44
	v_mov_b32_e32 v44, s66
	v_add_f32_e32 v45, 1.0, v45
	v_rcp_f32_e32 v46, v45
	v_add_f32_e32 v45, 1.0, v47
	v_rcp_f32_e32 v47, v45
	v_mov_b32_e32 v45, s67
	v_pk_add_f32 v[44:45], s[10:11], v[44:45]
	v_pk_mul_f32 v[42:43], v[42:43], v[46:47]
	v_add_f32_e32 v152, v44, v45
	v_pk_mul_f32 v[44:45], v[42:43], v[42:43]
	s_nop 0
	v_add_f32_e32 v44, v44, v45
	s_nop 1
	v_add_f32_dpp v44, v44, v44 row_ror:8 row_mask:0xf bank_mask:0xf bound_ctrl:1
	s_nop 1
	v_add_f32_dpp v44, v44, v44 row_ror:4 row_mask:0xf bank_mask:0xf bound_ctrl:1
	s_nop 1
	v_add_f32_dpp v44, v44, v44 row_ror:2 row_mask:0xf bank_mask:0xf bound_ctrl:1
	s_nop 1
	v_add_f32_dpp v44, v44, v44 row_ror:1 row_mask:0xf bank_mask:0xf bound_ctrl:1
	s_nop 0
	v_readlane_b32 s66, v44, 16
	v_readlane_b32 s67, v44, 48
	v_readlane_b32 s10, v44, 0
	v_readlane_b32 s11, v44, 32
	v_mov_b32_e32 v44, s66
	v_mov_b32_e32 v45, s67
	v_pk_add_f32 v[44:45], s[10:11], v[44:45]
	s_mov_b64 s[66:67], -1
	v_add_f32_e32 v44, v44, v45
	v_add_f32_e32 v45, 0x358637bd, v152
	v_mul_f32_e32 v46, 0x4b800000, v45
	v_cmp_gt_f32_e32 vcc, s81, v45
	v_add_f32_e32 v44, 0x358637bd, v44
	v_cmp_gt_f32_e64 s[10:11], s81, v44
	v_cndmask_b32_e32 v45, v45, v46, vcc
	v_rsq_f32_e32 v45, v45
	v_mul_f32_e32 v46, 0x4b800000, v44
	v_cndmask_b32_e64 v44, v44, v46, s[10:11]
	v_rsq_f32_e32 v44, v44
	v_mul_f32_e32 v46, 0x45800000, v45
	v_cndmask_b32_e32 v45, v45, v46, vcc
	v_mul_f32_e32 v45, 0x3db504f3, v45
	v_mul_f32_e32 v40, v40, v45
	v_mul_f32_e32 v41, v41, v45
	v_cvt_pk_bf16_f32 v40, v40, v41
	v_and_or_b32 v41, s65, 63, v201
	v_lshlrev_b32_e32 v41, 2, v41
	ds_bpermute_b32 v41, v41, v202
	v_mul_f32_e32 v46, 0x45800000, v44
	v_cndmask_b32_e64 v44, v44, v46, s[10:11]
	v_mul_f32_e32 v42, v42, v44
	v_mul_f32_e32 v43, v43, v44
	ds_write_b32 v204, v40 offset:1632
	v_cvt_pk_bf16_f32 v40, v42, v43
	ds_write_b32 v204, v40 offset:19040
	v_cvt_pk_bf16_f32 v40, v218, v219
	v_lshl_add_u32 v44, s65, 8, v203
	ds_write_b32 v44, v40
	s_waitcnt lgkmcnt(3)
	v_mul_f32_e32 v40, v42, v41
	v_mul_f32_e32 v41, v43, v41
	v_cvt_pk_bf16_f32 v40, v40, v41
	s_lshl_b32 s10, s90, 4
	v_and_or_b32 v35, v40, s79, v35
	v_lshl_or_b32 v39, v40, 16, v39
	v_mul_lo_u32 v40, v102, s82
	s_add_i32 s10, s10, s64
	v_add_u32_e32 v40, s10, v40
	ds_write_b128 v40, v[36:39] offset:34816
	ds_write_b128 v40, v[32:35] offset:34960
	s_waitcnt lgkmcnt(0)
	s_barrier
	s_mov_b64 exec, -1
	s_lshr_b32 s91, s90, 2
	s_lshr_b32 s92, s90, 1
	s_and_b32 s92, s92, 1
	s_and_b32 s10, s90, 1
	v_and_b32_e32 v210, 31, v206
	v_and_b32_e32 v211, 63, v206
	v_lshrrev_b32_e32 v211, 5, v211
	v_mov_b32_e32 v217, 0x110
	v_mul_u32_u24_e32 v215, v210, v217
	v_lshl_add_u32 v215, v211, 4, v215
	s_mul_i32 s11, s92, 0x2200
	s_cmp_eq_u32 s91, 0
	s_cselect_b32 s66, 0x4400, 0
	s_add_u32 s11, s11, s66
	v_add_u32_e32 v216, s11, v215
	s_mul_i32 s11, s10, 0x2200
	s_add_u32 s11, s11, 0x4400
	v_add_u32_e32 v215, s11, v215
	ds_read_b128 v[104:107], v216
	ds_read_b128 v[136:139], v215
	ds_read_b128 v[108:111], v216 offset:32
	ds_read_b128 v[140:143], v215 offset:32
	ds_read_b128 v[112:115], v216 offset:64
	ds_read_b128 v[144:147], v215 offset:64
	ds_read_b128 v[116:119], v216 offset:96
	ds_read_b128 v[148:151], v215 offset:96
	ds_read_b128 v[120:123], v216 offset:128
	ds_read_b128 v[152:155], v215 offset:128
	ds_read_b128 v[124:127], v216 offset:160
	ds_read_b128 v[156:159], v215 offset:160
	ds_read_b128 v[128:131], v216 offset:192
	ds_read_b128 v[160:163], v215 offset:192
	s_waitcnt lgkmcnt(10)
	ds_read_b128 v[132:135], v216 offset:224
	ds_read_b128 v[164:167], v215 offset:224
	s_lshl_b32 s11, s10, 5
	v_add_u32_e32 v212, s11, v210
	s_lshl_b32 s67, s92, 5
	v_lshl_add_u32 v217, v211, 2, s67
	v_sub_u32_e32 v213, v212, v217
	v_lshlrev_b32_e32 v216, 2, v217
	v_add_u32_e32 v216, 0x24400, v216
	v_lshlrev_b32_e32 v215, 2, v212
	v_add_u32_e32 v215, 0x24400, v215
	s_waitcnt lgkmcnt(14)
	v_mfma_f32_32x32x16_bf16 v[32:47], v[104:107], v[136:139], 0
	s_waitcnt lgkmcnt(12)
	v_mfma_f32_32x32x16_bf16 v[32:47], v[108:111], v[140:143], v[32:47]
	s_waitcnt lgkmcnt(10)
	v_mfma_f32_32x32x16_bf16 v[32:47], v[112:115], v[144:147], v[32:47]
	s_waitcnt lgkmcnt(8)
	v_mfma_f32_32x32x16_bf16 v[32:47], v[116:119], v[148:151], v[32:47]
	s_waitcnt lgkmcnt(6)
	v_mfma_f32_32x32x16_bf16 v[32:47], v[120:123], v[152:155], v[32:47]
	s_waitcnt lgkmcnt(4)
	v_mfma_f32_32x32x16_bf16 v[32:47], v[124:127], v[156:159], v[32:47]
	s_waitcnt lgkmcnt(2)
	v_mfma_f32_32x32x16_bf16 v[32:47], v[128:131], v[160:163], v[32:47]
	s_waitcnt lgkmcnt(0)
	v_mfma_f32_32x32x16_bf16 v[32:47], v[132:135], v[164:167], v[32:47]
	ds_read_b32 v214, v215
	ds_read_b128 v[168:171], v216
	ds_read_b128 v[172:175], v216 offset:32
	ds_read_b128 v[176:179], v216 offset:64
	ds_read_b128 v[180:183], v216 offset:96
	ds_read_b128 v[86:89], v216 offset:512
	ds_read_b128 v[90:93], v216 offset:544
	ds_read_b128 v[94:97], v216 offset:576
	ds_read_b128 v[98:101], v216 offset:608
	s_cmp_eq_u32 s91, 0
	s_cbranch_scc0 .Ldb_intra
	v_lshlrev_b32_e32 v218, 8, v217
	v_lshl_add_u32 v218, v212, 2, v218
	v_add_u32_e32 v218, 0x17c00, v218
	v_mov_b32_e32 v219, 0
	s_waitcnt lgkmcnt(0)
	v_sub_f32_e32 v220, v168, v214
	v_sub_f32_e32 v221, v169, v214
	v_sub_f32_e32 v222, v170, v214
	v_sub_f32_e32 v223, v171, v214
	v_sub_f32_e32 v224, v172, v214
	v_sub_f32_e32 v225, v173, v214
	v_sub_f32_e32 v226, v174, v214
	v_sub_f32_e32 v227, v175, v214
	v_sub_f32_e32 v228, v176, v214
	v_sub_f32_e32 v229, v177, v214
	v_sub_f32_e32 v230, v178, v214
	v_sub_f32_e32 v231, v179, v214
	v_sub_f32_e32 v232, v180, v214
	v_sub_f32_e32 v233, v181, v214
	v_sub_f32_e32 v234, v182, v214
	v_sub_f32_e32 v235, v183, v214
	v_mul_f32_e32 v220, 0x3fb8aa3b, v220
	v_mul_f32_e32 v221, 0x3fb8aa3b, v221
	v_mul_f32_e32 v222, 0x3fb8aa3b, v222
	v_mul_f32_e32 v223, 0x3fb8aa3b, v223
	v_mul_f32_e32 v224, 0x3fb8aa3b, v224
	v_mul_f32_e32 v225, 0x3fb8aa3b, v225
	v_mul_f32_e32 v226, 0x3fb8aa3b, v226
	v_mul_f32_e32 v227, 0x3fb8aa3b, v227
	v_mul_f32_e32 v228, 0x3fb8aa3b, v228
	v_mul_f32_e32 v229, 0x3fb8aa3b, v229
	v_mul_f32_e32 v230, 0x3fb8aa3b, v230
	v_mul_f32_e32 v231, 0x3fb8aa3b, v231
	v_mul_f32_e32 v232, 0x3fb8aa3b, v232
	v_mul_f32_e32 v233, 0x3fb8aa3b, v233
	v_mul_f32_e32 v234, 0x3fb8aa3b, v234
	v_mul_f32_e32 v235, 0x3fb8aa3b, v235
	v_exp_f32_e32 v220, v220
	v_exp_f32_e32 v221, v221
	v_exp_f32_e32 v222, v222
	v_exp_f32_e32 v223, v223
	v_exp_f32_e32 v224, v224
	v_exp_f32_e32 v225, v225
	v_exp_f32_e32 v226, v226
	v_exp_f32_e32 v227, v227
	v_exp_f32_e32 v228, v228
	v_exp_f32_e32 v229, v229
	v_exp_f32_e32 v230, v230
	v_exp_f32_e32 v231, v231
	v_exp_f32_e32 v232, v232
	v_exp_f32_e32 v233, v233
	v_exp_f32_e32 v234, v234
	v_exp_f32_e32 v235, v235
	s_nop 3
	v_mul_f32_e32 v32, v32, v86
	v_mul_f32_e32 v33, v33, v87
	v_mul_f32_e32 v34, v34, v88
	v_mul_f32_e32 v35, v35, v89
	v_mul_f32_e32 v36, v36, v90
	v_mul_f32_e32 v37, v37, v91
	v_mul_f32_e32 v38, v38, v92
	v_mul_f32_e32 v39, v39, v93
	v_mul_f32_e32 v40, v40, v94
	v_mul_f32_e32 v41, v41, v95
	v_mul_f32_e32 v42, v42, v96
	v_mul_f32_e32 v43, v43, v97
	v_mul_f32_e32 v44, v44, v98
	v_mul_f32_e32 v45, v45, v99
	v_mul_f32_e32 v46, v46, v100
	v_mul_f32_e32 v47, v47, v101
	v_cmp_gt_i32_e32 vcc, 0, v213
	v_mul_f32_e32 v32, v220, v32
	s_nop 0
	v_cndmask_b32_e32 v32, v219, v32, vcc
	ds_write_b32 v218, v32
	v_cmp_gt_i32_e32 vcc, 1, v213
	v_mul_f32_e32 v33, v221, v33
	s_nop 0
	v_cndmask_b32_e32 v33, v219, v33, vcc
	ds_write_b32 v218, v33 offset:256
	v_cmp_gt_i32_e32 vcc, 2, v213
	v_mul_f32_e32 v34, v222, v34
	s_nop 0
	v_cndmask_b32_e32 v34, v219, v34, vcc
	ds_write_b32 v218, v34 offset:512
	v_cmp_gt_i32_e32 vcc, 3, v213
	v_mul_f32_e32 v35, v223, v35
	s_nop 0
	v_cndmask_b32_e32 v35, v219, v35, vcc
	ds_write_b32 v218, v35 offset:768
	v_cmp_gt_i32_e32 vcc, 8, v213
	v_mul_f32_e32 v36, v224, v36
	s_nop 0
	v_cndmask_b32_e32 v36, v219, v36, vcc
	ds_write_b32 v218, v36 offset:2048
	v_cmp_gt_i32_e32 vcc, 9, v213
	v_mul_f32_e32 v37, v225, v37
	s_nop 0
	v_cndmask_b32_e32 v37, v219, v37, vcc
	ds_write_b32 v218, v37 offset:2304
	v_cmp_gt_i32_e32 vcc, 10, v213
	v_mul_f32_e32 v38, v226, v38
	s_nop 0
	v_cndmask_b32_e32 v38, v219, v38, vcc
	ds_write_b32 v218, v38 offset:2560
	v_cmp_gt_i32_e32 vcc, 11, v213
	v_mul_f32_e32 v39, v227, v39
	s_nop 0
	v_cndmask_b32_e32 v39, v219, v39, vcc
	ds_write_b32 v218, v39 offset:2816
	s_waitcnt lgkmcnt(0)
	v_cmp_gt_i32_e32 vcc, 16, v213
	v_mul_f32_e32 v40, v228, v40
	s_nop 0
	v_cndmask_b32_e32 v40, v219, v40, vcc
	ds_write_b32 v218, v40 offset:4096
	v_cmp_gt_i32_e32 vcc, 17, v213
	v_mul_f32_e32 v41, v229, v41
	s_nop 0
	v_cndmask_b32_e32 v41, v219, v41, vcc
	ds_write_b32 v218, v41 offset:4352
	v_cmp_gt_i32_e32 vcc, 18, v213
	v_mul_f32_e32 v42, v230, v42
	s_nop 0
	v_cndmask_b32_e32 v42, v219, v42, vcc
	ds_write_b32 v218, v42 offset:4608
	v_cmp_gt_i32_e32 vcc, 19, v213
	v_mul_f32_e32 v43, v231, v43
	s_nop 0
	v_cndmask_b32_e32 v43, v219, v43, vcc
	ds_write_b32 v218, v43 offset:4864
	v_cmp_gt_i32_e32 vcc, 24, v213
	v_mul_f32_e32 v44, v232, v44
	s_nop 0
	v_cndmask_b32_e32 v44, v219, v44, vcc
	ds_write_b32 v218, v44 offset:6144
	v_cmp_gt_i32_e32 vcc, 25, v213
	v_mul_f32_e32 v45, v233, v45
	s_nop 0
	v_cndmask_b32_e32 v45, v219, v45, vcc
	ds_write_b32 v218, v45 offset:6400
	v_cmp_gt_i32_e32 vcc, 26, v213
	v_mul_f32_e32 v46, v234, v46
	s_nop 0
	v_cndmask_b32_e32 v46, v219, v46, vcc
	ds_write_b32 v218, v46 offset:6656
	v_cmp_gt_i32_e32 vcc, 27, v213
	v_mul_f32_e32 v47, v235, v47
	s_nop 0
	v_cndmask_b32_e32 v47, v219, v47, vcc
	ds_write_b32 v218, v47 offset:6912
	s_branch .Ldb_done
.Ldb_intra:
	v_mov_b32_e32 v218, 0x90
	v_mul_u32_u24_e32 v218, v217, v218
	v_lshl_add_u32 v218, v212, 1, v218
	v_add_u32_e32 v218, 0x15800, v218
	v_mov_b32_e32 v219, 0
	s_waitcnt lgkmcnt(0)
	v_sub_f32_e32 v220, v168, v214
	v_sub_f32_e32 v221, v169, v214
	v_sub_f32_e32 v222, v170, v214
	v_sub_f32_e32 v223, v171, v214
	v_sub_f32_e32 v224, v172, v214
	v_sub_f32_e32 v225, v173, v214
	v_sub_f32_e32 v226, v174, v214
	v_sub_f32_e32 v227, v175, v214
	v_sub_f32_e32 v228, v176, v214
	v_sub_f32_e32 v229, v177, v214
	v_sub_f32_e32 v230, v178, v214
	v_sub_f32_e32 v231, v179, v214
	v_sub_f32_e32 v232, v180, v214
	v_sub_f32_e32 v233, v181, v214
	v_sub_f32_e32 v234, v182, v214
	v_sub_f32_e32 v235, v183, v214
	v_mul_f32_e32 v220, 0x3fb8aa3b, v220
	v_mul_f32_e32 v221, 0x3fb8aa3b, v221
	v_mul_f32_e32 v222, 0x3fb8aa3b, v222
	v_mul_f32_e32 v223, 0x3fb8aa3b, v223
	v_mul_f32_e32 v224, 0x3fb8aa3b, v224
	v_mul_f32_e32 v225, 0x3fb8aa3b, v225
	v_mul_f32_e32 v226, 0x3fb8aa3b, v226
	v_mul_f32_e32 v227, 0x3fb8aa3b, v227
	v_mul_f32_e32 v228, 0x3fb8aa3b, v228
	v_mul_f32_e32 v229, 0x3fb8aa3b, v229
	v_mul_f32_e32 v230, 0x3fb8aa3b, v230
	v_mul_f32_e32 v231, 0x3fb8aa3b, v231
	v_mul_f32_e32 v232, 0x3fb8aa3b, v232
	v_mul_f32_e32 v233, 0x3fb8aa3b, v233
	v_mul_f32_e32 v234, 0x3fb8aa3b, v234
	v_mul_f32_e32 v235, 0x3fb8aa3b, v235
	v_exp_f32_e32 v220, v220
	v_exp_f32_e32 v221, v221
	v_exp_f32_e32 v222, v222
	v_exp_f32_e32 v223, v223
	v_exp_f32_e32 v224, v224
	v_exp_f32_e32 v225, v225
	v_exp_f32_e32 v226, v226
	v_exp_f32_e32 v227, v227
	v_exp_f32_e32 v228, v228
	v_exp_f32_e32 v229, v229
	v_exp_f32_e32 v230, v230
	v_exp_f32_e32 v231, v231
	v_exp_f32_e32 v232, v232
	v_exp_f32_e32 v233, v233
	v_exp_f32_e32 v234, v234
	v_exp_f32_e32 v235, v235
	s_nop 3
	v_cmp_ge_i32_e32 vcc, 0, v213
	v_mul_f32_e32 v32, v32, v220
	s_nop 0
	v_cndmask_b32_e32 v32, v219, v32, vcc
	v_cvt_pk_bf16_f32 v32, v32, v219
	ds_write_b16 v218, v32
	v_cmp_ge_i32_e32 vcc, 1, v213
	v_mul_f32_e32 v33, v33, v221
	s_nop 0
	v_cndmask_b32_e32 v33, v219, v33, vcc
	v_cvt_pk_bf16_f32 v33, v33, v219
	ds_write_b16 v218, v33 offset:144
	v_cmp_ge_i32_e32 vcc, 2, v213
	v_mul_f32_e32 v34, v34, v222
	s_nop 0
	v_cndmask_b32_e32 v34, v219, v34, vcc
	v_cvt_pk_bf16_f32 v34, v34, v219
	ds_write_b16 v218, v34 offset:288
	v_cmp_ge_i32_e32 vcc, 3, v213
	v_mul_f32_e32 v35, v35, v223
	s_nop 0
	v_cndmask_b32_e32 v35, v219, v35, vcc
	v_cvt_pk_bf16_f32 v35, v35, v219
	ds_write_b16 v218, v35 offset:432
	v_cmp_ge_i32_e32 vcc, 8, v213
	v_mul_f32_e32 v36, v36, v224
	s_nop 0
	v_cndmask_b32_e32 v36, v219, v36, vcc
	v_cvt_pk_bf16_f32 v36, v36, v219
	ds_write_b16 v218, v36 offset:1152
	v_cmp_ge_i32_e32 vcc, 9, v213
	v_mul_f32_e32 v37, v37, v225
	s_nop 0
	v_cndmask_b32_e32 v37, v219, v37, vcc
	v_cvt_pk_bf16_f32 v37, v37, v219
	ds_write_b16 v218, v37 offset:1296
	v_cmp_ge_i32_e32 vcc, 10, v213
	v_mul_f32_e32 v38, v38, v226
	s_nop 0
	v_cndmask_b32_e32 v38, v219, v38, vcc
	v_cvt_pk_bf16_f32 v38, v38, v219
	ds_write_b16 v218, v38 offset:1440
	v_cmp_ge_i32_e32 vcc, 11, v213
	v_mul_f32_e32 v39, v39, v227
	s_nop 0
	v_cndmask_b32_e32 v39, v219, v39, vcc
	v_cvt_pk_bf16_f32 v39, v39, v219
	ds_write_b16 v218, v39 offset:1584
	s_waitcnt lgkmcnt(0)
	v_cmp_ge_i32_e32 vcc, 16, v213
	v_mul_f32_e32 v40, v40, v228
	s_nop 0
	v_cndmask_b32_e32 v40, v219, v40, vcc
	v_cvt_pk_bf16_f32 v40, v40, v219
	ds_write_b16 v218, v40 offset:2304
	v_cmp_ge_i32_e32 vcc, 17, v213
	v_mul_f32_e32 v41, v41, v229
	s_nop 0
	v_cndmask_b32_e32 v41, v219, v41, vcc
	v_cvt_pk_bf16_f32 v41, v41, v219
	ds_write_b16 v218, v41 offset:2448
	v_cmp_ge_i32_e32 vcc, 18, v213
	v_mul_f32_e32 v42, v42, v230
	s_nop 0
	v_cndmask_b32_e32 v42, v219, v42, vcc
	v_cvt_pk_bf16_f32 v42, v42, v219
	ds_write_b16 v218, v42 offset:2592
	v_cmp_ge_i32_e32 vcc, 19, v213
	v_mul_f32_e32 v43, v43, v231
	s_nop 0
	v_cndmask_b32_e32 v43, v219, v43, vcc
	v_cvt_pk_bf16_f32 v43, v43, v219
	ds_write_b16 v218, v43 offset:2736
	v_cmp_ge_i32_e32 vcc, 24, v213
	v_mul_f32_e32 v44, v44, v232
	s_nop 0
	v_cndmask_b32_e32 v44, v219, v44, vcc
	v_cvt_pk_bf16_f32 v44, v44, v219
	ds_write_b16 v218, v44 offset:3456
	v_cmp_ge_i32_e32 vcc, 25, v213
	v_mul_f32_e32 v45, v45, v233
	s_nop 0
	v_cndmask_b32_e32 v45, v219, v45, vcc
	v_cvt_pk_bf16_f32 v45, v45, v219
	ds_write_b16 v218, v45 offset:3600
	v_cmp_ge_i32_e32 vcc, 26, v213
	v_mul_f32_e32 v46, v46, v234
	s_nop 0
	v_cndmask_b32_e32 v46, v219, v46, vcc
	v_cvt_pk_bf16_f32 v46, v46, v219
	ds_write_b16 v218, v46 offset:3744
	v_cmp_ge_i32_e32 vcc, 27, v213
	v_mul_f32_e32 v47, v47, v235
	s_nop 0
	v_cndmask_b32_e32 v47, v219, v47, vcc
	v_cvt_pk_bf16_f32 v47, v47, v219
	ds_write_b16 v218, v47 offset:3888
.Ldb_done:
.LBB0_763:
	v_mov_b32_e32 v32, 0x17c00
	s_waitcnt lgkmcnt(0)
	v_mov_b32_e32 v33, 0x24400
	s_barrier
	s_mov_b64 exec, -1
	v_and_b32_e32 v201, 15, v206
	v_lshrrev_b32_e32 v212, 6, v206
	v_and_b32_e32 v210, 63, v206
	v_lshrrev_b32_e32 v210, 4, v210
	v_readfirstlane_b32 s91, v212
	s_nop 7
	s_nop 7
	s_and_b32 s92, s91, 3
	s_lshl_b32 s92, s92, 6
	v_lshlrev_b32_e32 v211, 1, v201
	v_lshrrev_b32_e32 v212, 6, v206
	v_and_b32_e32 v212, 3, v212
	v_lshl_add_u32 v211, v212, 6, v211
	v_lshlrev_b32_e32 v190, 4, v210
	v_add_u32_e32 v190, 0x24400, v190
	ds_read_b128 v[90:93], v190 offset:512
	ds_read_b128 v[94:97], v190 offset:576
	ds_read_b128 v[98:101], v190 offset:640
	ds_read_b128 v[246:249], v190 offset:704
	s_cmp_ge_u32 s91, 4
	s_cbranch_scc1 .Ldm_kinit
	v_lshl_add_u32 v255, v210, 10, v211
	v_add_u32_e32 v255, 0x1fc00, v255
	v_lshl_add_u32 v245, v210, 10, v211
	v_add_u32_e32 v245, 0x1bc00, v245
	ds_read_u16 v213, v255
	ds_read_u16 v214, v255 offset:256
	ds_read_u16 v215, v255 offset:512
	ds_read_u16 v216, v255 offset:768
	ds_read_u16 v217, v255 offset:32
	ds_read_u16 v218, v255 offset:288
	ds_read_u16 v219, v255 offset:544
	ds_read_u16 v220, v255 offset:800
	s_waitcnt lgkmcnt(0)
	ds_read_u16 v221, v255 offset:4096
	ds_read_u16 v222, v255 offset:4352
	ds_read_u16 v223, v255 offset:4608
	ds_read_u16 v224, v255 offset:4864
	ds_read_u16 v225, v255 offset:4128
	ds_read_u16 v226, v255 offset:4384
	ds_read_u16 v227, v255 offset:4640
	ds_read_u16 v228, v255 offset:4896
	v_lshlrev_b32_e32 v213, 16, v213
	v_lshlrev_b32_e32 v214, 16, v214
	v_lshlrev_b32_e32 v215, 16, v215
	v_lshlrev_b32_e32 v216, 16, v216
	v_lshlrev_b32_e32 v217, 16, v217
	v_lshlrev_b32_e32 v218, 16, v218
	v_lshlrev_b32_e32 v219, 16, v219
	v_lshlrev_b32_e32 v220, 16, v220
	v_mul_f32_e32 v104, v90, v213
	v_sub_f32_e32 v104, 0, v104
	v_mul_f32_e32 v105, v91, v214
	v_sub_f32_e32 v105, 0, v105
	v_mul_f32_e32 v106, v92, v215
	v_sub_f32_e32 v106, 0, v106
	v_mul_f32_e32 v107, v93, v216
	v_sub_f32_e32 v107, 0, v107
	v_mul_f32_e32 v108, v90, v217
	v_sub_f32_e32 v108, 0, v108
	v_mul_f32_e32 v109, v91, v218
	v_sub_f32_e32 v109, 0, v109
	v_mul_f32_e32 v110, v92, v219
	v_sub_f32_e32 v110, 0, v110
	v_mul_f32_e32 v111, v93, v220
	v_sub_f32_e32 v111, 0, v111
	s_waitcnt lgkmcnt(0)
	ds_read_u16 v229, v255 offset:8192
	ds_read_u16 v230, v255 offset:8448
	ds_read_u16 v231, v255 offset:8704
	ds_read_u16 v232, v255 offset:8960
	ds_read_u16 v233, v255 offset:8224
	ds_read_u16 v234, v255 offset:8480
	ds_read_u16 v235, v255 offset:8736
	ds_read_u16 v236, v255 offset:8992
	v_lshlrev_b32_e32 v221, 16, v221
	v_lshlrev_b32_e32 v222, 16, v222
	v_lshlrev_b32_e32 v223, 16, v223
	v_lshlrev_b32_e32 v224, 16, v224
	v_lshlrev_b32_e32 v225, 16, v225
	v_lshlrev_b32_e32 v226, 16, v226
	v_lshlrev_b32_e32 v227, 16, v227
	v_lshlrev_b32_e32 v228, 16, v228
	v_mul_f32_e32 v112, v94, v221
	v_sub_f32_e32 v112, 0, v112
	v_mul_f32_e32 v113, v95, v222
	v_sub_f32_e32 v113, 0, v113
	v_mul_f32_e32 v114, v96, v223
	v_sub_f32_e32 v114, 0, v114
	v_mul_f32_e32 v115, v97, v224
	v_sub_f32_e32 v115, 0, v115
	v_mul_f32_e32 v116, v94, v225
	v_sub_f32_e32 v116, 0, v116
	v_mul_f32_e32 v117, v95, v226
	v_sub_f32_e32 v117, 0, v117
	v_mul_f32_e32 v118, v96, v227
	v_sub_f32_e32 v118, 0, v118
	v_mul_f32_e32 v119, v97, v228
	v_sub_f32_e32 v119, 0, v119
	s_waitcnt lgkmcnt(0)
	ds_read_u16 v237, v255 offset:12288
	ds_read_u16 v238, v255 offset:12544
	ds_read_u16 v239, v255 offset:12800
	ds_read_u16 v240, v255 offset:13056
	ds_read_u16 v241, v255 offset:12320
	ds_read_u16 v242, v255 offset:12576
	ds_read_u16 v243, v255 offset:12832
	ds_read_u16 v244, v255 offset:13088
	v_lshlrev_b32_e32 v229, 16, v229
	v_lshlrev_b32_e32 v230, 16, v230
	v_lshlrev_b32_e32 v231, 16, v231
	v_lshlrev_b32_e32 v232, 16, v232
	v_lshlrev_b32_e32 v233, 16, v233
	v_lshlrev_b32_e32 v234, 16, v234
	v_lshlrev_b32_e32 v235, 16, v235
	v_lshlrev_b32_e32 v236, 16, v236
	v_mul_f32_e32 v120, v98, v229
	v_sub_f32_e32 v120, 0, v120
	v_mul_f32_e32 v121, v99, v230
	v_sub_f32_e32 v121, 0, v121
	v_mul_f32_e32 v122, v100, v231
	v_sub_f32_e32 v122, 0, v122
	v_mul_f32_e32 v123, v101, v232
	v_sub_f32_e32 v123, 0, v123
	v_mul_f32_e32 v124, v98, v233
	v_sub_f32_e32 v124, 0, v124
	v_mul_f32_e32 v125, v99, v234
	v_sub_f32_e32 v125, 0, v125
	v_mul_f32_e32 v126, v100, v235
	v_sub_f32_e32 v126, 0, v126
	v_mul_f32_e32 v127, v101, v236
	v_sub_f32_e32 v127, 0, v127
	s_waitcnt lgkmcnt(0)
	v_lshlrev_b32_e32 v237, 16, v237
	v_lshlrev_b32_e32 v238, 16, v238
	v_lshlrev_b32_e32 v239, 16, v239
	v_lshlrev_b32_e32 v240, 16, v240
	v_lshlrev_b32_e32 v241, 16, v241
	v_lshlrev_b32_e32 v242, 16, v242
	v_lshlrev_b32_e32 v243, 16, v243
	v_lshlrev_b32_e32 v244, 16, v244
	v_mul_f32_e32 v128, v246, v237
	v_sub_f32_e32 v128, 0, v128
	v_mul_f32_e32 v129, v247, v238
	v_sub_f32_e32 v129, 0, v129
	v_mul_f32_e32 v130, v248, v239
	v_sub_f32_e32 v130, 0, v130
	v_mul_f32_e32 v131, v249, v240
	v_sub_f32_e32 v131, 0, v131
	v_mul_f32_e32 v132, v246, v241
	v_sub_f32_e32 v132, 0, v132
	v_mul_f32_e32 v133, v247, v242
	v_sub_f32_e32 v133, 0, v133
	v_mul_f32_e32 v134, v248, v243
	v_sub_f32_e32 v134, 0, v134
	v_mul_f32_e32 v135, v249, v244
	v_sub_f32_e32 v135, 0, v135
	s_branch .Ldm_inited
